# MLA units: next-unit prefetch (K/ropeK/V first pair + Q into idle VGPRs + rope cos/sin rows via LDS-DMA) on top of FoX prefetch
# speedup vs baseline: 1.0020x; 1.0020x over previous
.LBB0_269:
	s_or_b64 exec, exec, s[4:5]
	v_readlane_b32 s4, v253, 19
	s_waitcnt lgkmcnt(0)
	s_barrier
	v_mov_b32_e32 v0, s4
	ds_read_b32 v0, v0
	s_waitcnt lgkmcnt(0)
	v_cmp_lt_i32_e32 vcc, s45, v0
	v_readfirstlane_b32 s37, v0
	s_cbranch_vccnz .LBB0_312
	s_mov_b32 s32, 0
	s_mov_b32 s44, 0
	s_branch .LBB0_272

.LBB0_291:
	v_mov_b32_e32 v2, v216
	s_and_b32 s38, s37, 7
	v_readfirstlane_b32 s18, v2
	s_lshl_b32 s4, s37, 9
	v_and_b32_e32 v6, 63, v2
	s_ashr_i32 s19, s18, 6
	s_and_b32 s4, s4, 0x7000
	s_lshl_b32 s5, s38, 8
	v_readlane_b32 s8, v255, 20
	s_add_u32 s8, s8, s5
	v_readlane_b32 s5, v255, 21
	v_or_b32_e32 v3, s4, v6
	s_addc_u32 s9, s5, 0
	v_lshlrev_b32_e32 v192, 11, v3
	s_lshl_b32 s12, s19, 3
	v_lshl_add_u64 v[0:1], s[8:9], 0, v[192:193]
	s_ashr_i32 s13, s12, 31
	v_lshl_add_u64 v[138:139], s[12:13], 1, v[0:1]
	v_readlane_b32 s12, v255, 22
	v_lshlrev_b32_e32 v192, 6, v3
	v_readlane_b32 s13, v255, 23
	s_and_b32 s20, s19, 3
	s_lshl_b32 s39, s19, 10
	v_lshl_add_u64 v[0:1], s[12:13], 0, v[192:193]
	s_lshl_b32 s34, s20, 4
	s_add_i32 s5, s39, 0
	s_cmp_lg_u32 s32, 0
	s_cbranch_scc1 .Lpf0_s0
	s_mov_b32 s12, m0
	s_mov_b32 m0, s5
	s_nop 0
	global_load_lds_dwordx4 v[138:139], off
	s_mov_b32 m0, s12
.Lpf0_s0:
	s_cmp_lt_i32 s19, 4
	v_lshl_add_u64 v[140:141], v[0:1], 0, s[34:35]
	s_cselect_b64 s[28:29], -1, 0
	s_cmp_gt_i32 s19, 3
	s_cbranch_scc1 .LBB0_293
	s_add_i32 s12, s5, 0x2000
	s_cmp_lg_u32 s32, 0
	s_cbranch_scc1 .Lpf0_s1
	s_mov_b32 s13, m0
	s_mov_b32 m0, s12
	s_nop 0
	global_load_lds_dwordx4 v[140:141], off
	s_mov_b32 m0, s13
.Lpf0_s1:
.LBB0_293:
	v_lshrrev_b32_e32 v0, 2, v6
	v_lshl_or_b32 v0, s20, 4, v0
	v_or_b32_e32 v0, s4, v0
	v_lshlrev_b32_e32 v192, 11, v0
	s_ashr_i32 s12, s18, 8
	v_lshl_add_u64 v[0:1], s[8:9], 0, v[192:193]
	s_lshl_b32 s8, s12, 5
	s_ashr_i32 s9, s8, 31
	v_lshlrev_b32_e32 v3, 3, v2
	v_lshl_add_u64 v[0:1], s[8:9], 1, v[0:1]
	v_and_b32_e32 v3, 24, v3
	s_lshl_b32 s8, s12, 12
	s_lshl_b32 s9, s20, 10
	v_lshlrev_b32_e32 v192, 1, v3
	s_or_b32 s8, s9, s8
	v_lshl_add_u64 v[0:1], v[0:1], 0, v[192:193]
	s_add_i32 s9, s8, 0
	v_lshl_add_u64 v[142:143], v[0:1], 0, s[24:25]
	s_add_i32 s36, s9, 0xc000
	s_cmp_lg_u32 s32, 0
	s_cbranch_scc1 .Lpf0_s2
	s_mov_b32 s8, m0
	s_mov_b32 m0, s36
	s_nop 0
	global_load_lds_dwordx4 v[142:143], off
	s_mov_b32 m0, s8
.Lpf0_s2:
	s_mov_b64 s[12:13], 0x20000
	v_lshl_add_u64 v[0:1], v[138:139], 0, s[12:13]
	s_add_i32 s8, s5, 0x3000
	s_cmp_lg_u32 s32, 0
	s_cbranch_scc1 .Lpf0_s3
	s_mov_b32 s12, m0
	s_mov_b32 m0, s8
	s_nop 0
	global_load_lds_dwordx4 v[0:1], off
	s_mov_b32 m0, s12
.Lpf0_s3:
	v_cndmask_b32_e64 v4, 0, 1, s[28:29]
	v_cmp_ne_u32_e64 s[42:43], 1, v4
	s_andn2_b64 vcc, exec, s[28:29]
	s_cbranch_vccnz .LBB0_295
	s_mov_b64 s[12:13], 0x1000
	s_addk_i32 s5, 0x5000
	v_lshl_add_u64 v[0:1], v[140:141], 0, s[12:13]
	s_cmp_lg_u32 s32, 0
	s_cbranch_scc1 .Lpf0_s4
	s_mov_b32 s8, m0
	s_mov_b32 m0, s5
	s_nop 0
	global_load_lds_dwordx4 v[0:1], off
	s_mov_b32 m0, s8
.Lpf0_s4:
.LBB0_295:
	s_ashr_i32 s5, s37, 6
	s_sub_i32 s8, 15, s5
	s_lshl_b32 s12, s8, 8
	s_lshl_b32 s13, s19, 5
	v_and_b32_e32 v4, 31, v2
	s_add_i32 s13, s13, s12
	v_or_b32_e32 v16, s13, v4
	s_mul_i32 s12, s38, 0xc0
	v_readlane_b32 s13, v255, 4
	s_add_u32 s12, s13, s12
	v_readlane_b32 s13, v255, 5
	s_mov_b64 s[14:15], 0x20000
	s_mov_b32 s5, s35
	s_addc_u32 s13, s13, 0
	v_lshl_add_u64 v[0:1], v[142:143], 0, s[14:15]
	s_add_i32 s9, s9, 0xe000
	v_ashrrev_i32_e32 v17, 31, v16
	s_ashr_i32 s28, s18, 7
	s_cmp_lg_u32 s32, 0
	s_cbranch_scc1 .Lpf0_s5
	s_mov_b32 s18, m0
	s_mov_b32 m0, s9
	s_nop 0
	global_load_lds_dwordx4 v[0:1], off
	s_mov_b32 m0, s18
.Lpf0_s5:
	v_lshl_add_u64 v[144:145], v[16:17], 0, s[4:5]
	v_mov_b64_e32 v[0:1], s[12:13]
	s_movk_i32 s9, 0x600
	v_mad_u64_u32 v[0:1], s[4:5], v144, s9, v[0:1]
	v_lshlrev_b32_e32 v16, 4, v16
	v_lshrrev_b32_e32 v5, 5, v6
	v_ashrrev_i32_e32 v17, 31, v16
	v_readlane_b32 s4, v255, 24
	v_mad_i32_i24 v1, v145, s9, v1
	v_lshlrev_b32_e32 v192, 4, v5
	v_lshlrev_b64 v[24:25], 2, v[16:17]
	v_readlane_b32 s5, v255, 25
	v_lshl_add_u64 v[0:1], v[0:1], 0, v[192:193]
	v_and_b32_e32 v192, 32, v6
	v_lshl_add_u64 v[16:17], s[4:5], 0, v[24:25]
	v_readlane_b32 s4, v255, 26
	v_lshl_add_u64 v[6:7], v[16:17], 0, v[192:193]
	v_readlane_b32 s5, v255, 27
	s_cmp_lg_u32 s32, 0
	s_cbranch_scc1 .Lpf0_q1
	global_load_dwordx4 v[8:11], v[0:1], off offset:128
	global_load_dwordx4 v[12:15], v[0:1], off offset:160
	global_load_dwordx4 v[16:19], v[6:7], off offset:16
	global_load_dwordx4 v[20:23], v[6:7], off
	v_lshl_add_u64 v[6:7], s[4:5], 0, v[24:25]
	v_lshl_add_u64 v[6:7], v[6:7], 0, v[192:193]
	global_load_dwordx4 v[24:27], v[6:7], off offset:16
	global_load_dwordx4 v[28:31], v[6:7], off
	global_load_dwordx4 v[88:91], v[0:1], off
	global_load_dwordx4 v[92:95], v[0:1], off offset:32
	global_load_dwordx4 v[96:99], v[0:1], off offset:64
	global_load_dwordx4 v[100:103], v[0:1], off offset:96
	s_branch .Lpf0_q2
.Lpf0_q1:
	v_mov_b32_e32 v88, v174
	v_mov_b32_e32 v89, v175
	v_mov_b32_e32 v90, v176
	v_mov_b32_e32 v91, v177
	v_mov_b32_e32 v92, v178
	v_mov_b32_e32 v93, v179
	v_mov_b32_e32 v94, v180
	v_mov_b32_e32 v95, v181
	v_mov_b32_e32 v96, v182
	v_mov_b32_e32 v97, v183
	v_mov_b32_e32 v98, v184
	v_mov_b32_e32 v99, v185
	v_mov_b32_e32 v100, v186
	v_mov_b32_e32 v101, v187
	v_mov_b32_e32 v102, v188
	v_mov_b32_e32 v103, v189
	v_mov_b32_e32 v8, v242
	v_mov_b32_e32 v9, v243
	v_mov_b32_e32 v10, v244
	v_mov_b32_e32 v11, v245
	v_mov_b32_e32 v12, v246
	v_mov_b32_e32 v13, v247
	v_mov_b32_e32 v14, v248
	v_mov_b32_e32 v15, v249
	v_and_b32_e32 v34, 63, v216
	v_lshlrev_b32_e32 v34, 4, v34
	s_lshl_b32 vcc_lo, s19, 12
	s_add_i32 vcc_lo, vcc_lo, 0x16000
	v_add_u32_e32 v34, vcc_lo, v34
	ds_read_b128 v[20:23], v34
	ds_read_b128 v[16:19], v34 offset:1024
	ds_read_b128 v[28:31], v34 offset:2048
	ds_read_b128 v[24:27], v34 offset:3072
	s_waitcnt lgkmcnt(0)
.Lpf0_q2:
	s_mov_b32 s32, 0
	v_mov_b32_e32 v0, v193
	v_lshlrev_b32_e32 v1, 4, v4
	v_lshlrev_b32_e32 v136, 2, v5
	v_lshrrev_b32_e32 v4, 2, v2
	v_and_or_b32 v4, v4, 3, v136
	v_lshlrev_b32_e32 v2, 1, v2
	s_lshl_b32 s8, s8, 2
	v_and_b32_e32 v2, 32, v2
	v_mov_b32_e32 v192, v193
	s_add_i32 s28, s28, s8
	s_add_i32 s8, s8, 4
	v_mov_b32_e32 v194, v193
	v_mov_b32_e32 v195, v193
	v_mov_b32_e32 v196, v193
	v_mov_b32_e32 v197, v193
	v_mov_b32_e32 v198, v193
	v_mov_b32_e32 v199, v193
	v_mov_b32_e32 v200, v193
	v_mov_b32_e32 v201, v193
	v_mov_b32_e32 v202, v193
	v_mov_b32_e32 v203, v193
	v_mov_b32_e32 v204, v193
	v_mov_b32_e32 v205, v193
	v_mov_b32_e32 v206, v193
	v_mov_b32_e32 v207, v193
	s_mov_b32 s18, 0
	s_lshr_b32 s19, s8, 1
	s_add_i32 s20, s39, 0x2000
	v_mov_b32_e32 v148, 0
	s_waitcnt vmcnt(3)
	v_lshlrev_b32_e32 v32, 16, v12
	v_and_b32_e32 v33, 0xffff0000, v12
	v_lshlrev_b32_e32 v6, 16, v8
	v_and_b32_e32 v7, 0xffff0000, v8
	v_pk_mul_f32 v[34:35], v[28:29], v[32:33]
	v_lshlrev_b32_e32 v8, 16, v13
	v_pk_fma_f32 v[34:35], v[20:21], v[6:7], v[34:35] neg_lo:[0,0,1] neg_hi:[0,0,1]
	v_pk_mul_f32 v[6:7], v[28:29], v[6:7]
	v_cvt_pk_bf16_f32 v80, v34, v35
	v_pk_fma_f32 v[6:7], v[20:21], v[32:33], v[6:7]
	v_mov_b32_e32 v32, v193
	v_cvt_pk_bf16_f32 v84, v6, v7
	v_lshlrev_b32_e32 v6, 16, v9
	v_and_b32_e32 v7, 0xffff0000, v9
	v_and_b32_e32 v9, 0xffff0000, v13
	v_pk_mul_f32 v[12:13], v[30:31], v[8:9]
	s_waitcnt vmcnt(2)
	s_waitcnt vmcnt(1)
	s_waitcnt vmcnt(0)
	v_pk_fma_f32 v[12:13], v[22:23], v[6:7], v[12:13] neg_lo:[0,0,1] neg_hi:[0,0,1]
	v_pk_mul_f32 v[6:7], v[30:31], v[6:7]
	v_cvt_pk_bf16_f32 v81, v12, v13
	v_pk_fma_f32 v[6:7], v[22:23], v[8:9], v[6:7]
	v_lshlrev_b32_e32 v8, 16, v14
	v_and_b32_e32 v9, 0xffff0000, v14
	v_cvt_pk_bf16_f32 v85, v6, v7
	v_lshlrev_b32_e32 v6, 16, v10
	v_and_b32_e32 v7, 0xffff0000, v10
	v_pk_mul_f32 v[12:13], v[24:25], v[8:9]
	s_nop 0
	v_pk_fma_f32 v[12:13], v[16:17], v[6:7], v[12:13] neg_lo:[0,0,1] neg_hi:[0,0,1]
	v_pk_mul_f32 v[6:7], v[24:25], v[6:7]
	v_cvt_pk_bf16_f32 v82, v12, v13
	v_pk_fma_f32 v[6:7], v[16:17], v[8:9], v[6:7]
	v_lshlrev_b32_e32 v8, 16, v15
	v_and_b32_e32 v9, 0xffff0000, v15
	v_cvt_pk_bf16_f32 v86, v6, v7
	v_lshlrev_b32_e32 v6, 16, v11
	v_and_b32_e32 v7, 0xffff0000, v11
	v_pk_mul_f32 v[10:11], v[26:27], v[8:9]
	s_nop 0
	v_pk_fma_f32 v[10:11], v[18:19], v[6:7], v[10:11] neg_lo:[0,0,1] neg_hi:[0,0,1]
	v_pk_mul_f32 v[6:7], v[26:27], v[6:7]
	v_cvt_pk_bf16_f32 v83, v10, v11
	v_pk_fma_f32 v[6:7], v[18:19], v[8:9], v[6:7]
	v_mov_b64_e32 v[16:17], v[192:193]
	v_cvt_pk_bf16_f32 v87, v6, v7
	s_waitcnt vmcnt(0)
	v_readfirstlane_b32 vcc_lo, v216
	s_cmp_lt_u32 vcc_lo, 64
	s_cbranch_scc0 .Lpf0_nosu
	v_readfirstlane_b32 vcc_lo, v146
	s_xor_b32 vcc_hi, s44, 1
	s_lshl_b32 vcc_hi, vcc_hi, 2
	s_add_i32 vcc_hi, vcc_hi, 0x15500
	v_mov_b32_e32 v48, vcc_hi
	v_mov_b32_e32 v49, vcc_lo
	ds_write_b32 v48, v49
.Lpf0_nosu:
	s_waitcnt vmcnt(0) lgkmcnt(0)
	s_barrier
	v_mov_b64_e32 v[18:19], v[194:195]
	v_lshlrev_b32_e32 v0, 10, v5
	v_add3_u32 v137, 0, v0, v1
	v_lshl_add_u32 v0, v4, 6, 0
	v_add3_u32 v147, v0, v2, v3
	v_mov_b64_e32 v[0:1], v[192:193]
	v_mov_b32_e32 v33, v32
	v_mov_b32_e32 v34, v32
	v_mov_b32_e32 v35, v32
	v_mov_b32_e32 v36, v32
	v_mov_b32_e32 v37, v32
	v_mov_b32_e32 v38, v32
	v_mov_b32_e32 v39, v32
	v_mov_b32_e32 v40, v32
	v_mov_b32_e32 v41, v32
	v_mov_b32_e32 v42, v32
	v_mov_b32_e32 v43, v32
	v_mov_b32_e32 v44, v32
	v_mov_b32_e32 v45, v32
	v_mov_b32_e32 v46, v32
	v_mov_b32_e32 v47, v32
	v_mov_b64_e32 v[20:21], v[196:197]
	v_mov_b64_e32 v[22:23], v[198:199]
	v_mov_b64_e32 v[24:25], v[200:201]
	v_mov_b64_e32 v[26:27], v[202:203]
	v_mov_b64_e32 v[28:29], v[204:205]
	v_mov_b64_e32 v[30:31], v[206:207]
	v_mov_b64_e32 v[2:3], v[194:195]
	v_mov_b64_e32 v[4:5], v[196:197]
	v_mov_b64_e32 v[6:7], v[198:199]
	v_mov_b64_e32 v[8:9], v[200:201]
	v_mov_b64_e32 v[10:11], v[202:203]
	v_mov_b64_e32 v[12:13], v[204:205]
	v_mov_b64_e32 v[14:15], v[206:207]
	s_branch .LBB0_297
.Lpf0_block:
	s_xor_b32 s4, s44, 1
	s_lshl_b32 s4, s4, 2
	s_add_i32 s4, s4, 0x15500
	v_mov_b32_e32 v48, s4
	ds_read_b32 v48, v48
	s_waitcnt lgkmcnt(0)
	v_readfirstlane_b32 s4, v48
	s_cmp_lt_u32 s4, 0x400
	s_cbranch_scc0 .LBB0_303
	s_mov_b32 s32, 1
	s_and_b32 s5, s4, 7
	s_lshr_b32 s8, s4, 3
	s_and_b32 s8, s8, 7
	s_lshl_b32 s8, s8, 12
	s_lshr_b32 s4, s4, 6
	s_sub_i32 s4, 15, s4
	v_lshrrev_b32_e32 v49, 6, v216
	v_and_b32_e32 v50, 63, v216
	v_readlane_b32 vcc_lo, v255, 20
	v_readlane_b32 vcc_hi, v255, 21
	s_lshl_b32 s9, s5, 8
	s_lshl_b32 s12, s8, 11
	s_add_u32 s9, s9, s12
	s_add_u32 vcc_lo, vcc_lo, s9
	s_addc_u32 vcc_hi, vcc_hi, 0
	v_lshlrev_b32_e32 v48, 11, v50
	v_lshl_or_b32 v48, v49, 4, v48
	s_mov_b32 m0, s39
	s_nop 0
	global_load_lds_dwordx4 v48, vcc
	s_add_u32 vcc_lo, vcc_lo, 0x20000
	s_addc_u32 vcc_hi, vcc_hi, 0
	s_add_i32 m0, s39, 0x3000
	s_nop 0
	global_load_lds_dwordx4 v48, vcc
	v_readlane_b32 vcc_lo, v255, 20
	v_readlane_b32 vcc_hi, v255, 21
	s_add_u32 vcc_lo, vcc_lo, s9
	s_addc_u32 vcc_hi, vcc_hi, 0
	s_add_u32 vcc_lo, vcc_lo, 0x80
	s_addc_u32 vcc_hi, vcc_hi, 0
	v_lshrrev_b32_e32 v51, 2, v50
	v_and_b32_e32 v52, 3, v49
	v_lshl_or_b32 v51, v52, 4, v51
	v_lshlrev_b32_e32 v51, 11, v51
	v_lshrrev_b32_e32 v53, 2, v49
	v_lshl_or_b32 v51, v53, 6, v51
	v_and_b32_e32 v53, 3, v50
	v_lshl_or_b32 v51, v53, 4, v51
	s_mov_b32 m0, s36
	s_nop 0
	global_load_lds_dwordx4 v51, vcc
	s_add_u32 vcc_lo, vcc_lo, 0x20000
	s_addc_u32 vcc_hi, vcc_hi, 0
	s_add_i32 m0, s36, 0x2000
	s_nop 0
	global_load_lds_dwordx4 v51, vcc
	s_cmp_lg_u64 s[42:43], 0
	s_cbranch_scc1 .Lpf0_norope
	v_readlane_b32 vcc_lo, v255, 22
	v_readlane_b32 vcc_hi, v255, 23
	s_lshl_b32 s12, s8, 6
	s_add_u32 vcc_lo, vcc_lo, s12
	s_addc_u32 vcc_hi, vcc_hi, 0
	v_lshlrev_b32_e32 v51, 6, v50
	v_lshl_or_b32 v51, v52, 4, v51
	s_mov_b32 m0, s20
	s_nop 0
	global_load_lds_dwordx4 v51, vcc
	s_add_u32 vcc_lo, vcc_lo, 0x1000
	s_addc_u32 vcc_hi, vcc_hi, 0
	s_add_i32 m0, s20, 0x3000
	s_nop 0
	global_load_lds_dwordx4 v51, vcc
.Lpf0_norope:
	v_readlane_b32 vcc_lo, v255, 4
	v_readlane_b32 vcc_hi, v255, 5
	s_lshl_b32 s12, s4, 8
	s_add_i32 s8, s8, s12
	s_mul_i32 s9, s8, 0x600
	s_mul_i32 s5, s5, 0xc0
	s_add_u32 s9, s9, s5
	s_add_u32 vcc_lo, vcc_lo, s9
	s_addc_u32 vcc_hi, vcc_hi, 0
	v_and_b32_e32 v51, 31, v216
	v_lshl_or_b32 v51, v49, 5, v51
	v_mul_u32_u24_e32 v53, 0x600, v51
	v_bfe_u32 v52, v216, 5, 1
	v_lshl_or_b32 v53, v52, 4, v53
	global_load_dwordx4 v[174:177], v53, vcc
	global_load_dwordx4 v[178:181], v53, vcc offset:32
	global_load_dwordx4 v[182:185], v53, vcc offset:64
	global_load_dwordx4 v[186:189], v53, vcc offset:96
	global_load_dwordx4 v[242:245], v53, vcc offset:128
	global_load_dwordx4 v[246:249], v53, vcc offset:160
	v_readlane_b32 vcc_lo, v255, 24
	v_readlane_b32 vcc_hi, v255, 25
	s_lshl_b32 s12, s12, 6
	s_add_u32 vcc_lo, vcc_lo, s12
	s_addc_u32 vcc_hi, vcc_hi, 0
	v_lshlrev_b32_e32 v53, 6, v51
	v_lshl_or_b32 v53, v52, 5, v53
	v_readfirstlane_b32 s9, v49
	s_lshl_b32 s9, s9, 12
	s_add_i32 s9, s9, 0x16000
	s_mov_b32 m0, s9
	v_add_u32_e32 v54, 16, v53
	global_load_lds_dwordx4 v53, vcc
	s_add_i32 m0, s9, 0x400
	s_nop 0
	global_load_lds_dwordx4 v54, vcc
	v_readlane_b32 vcc_lo, v255, 26
	v_readlane_b32 vcc_hi, v255, 27
	s_add_u32 vcc_lo, vcc_lo, s12
	s_addc_u32 vcc_hi, vcc_hi, 0
	s_add_i32 m0, s9, 0x800
	s_nop 0
	global_load_lds_dwordx4 v53, vcc
	s_add_i32 m0, s9, 0xc00
	s_nop 0
	global_load_lds_dwordx4 v54, vcc
	s_branch .LBB0_303
